# merge phase: per-XCD dynamic item queues (XCC_ID selects the queue) so the 8 N-tiles of an M-tile run on one XCD and its L2 serves the re-read xn / G row tiles; both layers dynamic
# speedup vs baseline: 1.0149x; 1.0092x over previous
; DI void phase_merge(const Params& p, int l, char* smem, int tid) {
;   const int lane = tid & 63, w = tid >> 6, r = lane & 31, h = lane >> 5, wm = w >> 1, wn = w & 1;
;   GemmLds* s = (GemmLds*)smem;
;   u16* ACC = p.Pk;
;   const bool dyn = (l == 0);
;   unsigned* qc = p.bar + 4096 + 320;
;   for (int it = (dyn ? fetch_item(qc, smem) : (int)blockIdx.x); it < 544 * 8; it = (dyn ? fetch_item(qc, smem) : it + (int)gridDim.x)) {
;     const int mt = it >> 3, nt = it & 7, m0 = mt * 64, n0 = nt * 128;
;     if (l == 1 && (mt % 68) < 4) continue;
.Lmg_item:
	s_barrier
	s_cmp_eq_u32 s10, 0
	s_cbranch_scc0 .Lmgx_wait
	s_mov_b64 s[6:7], exec
	s_mov_b64 exec, 1
	s_getreg_b32 s8, hwreg(HW_REG_XCC_ID, 0, 4)
	s_lshl_b32 s8, s8, 8
	s_lshl_b32 s9, s18, 11
	s_add_u32 s8, s8, s9
	s_add_u32 s8, s8, 0x1da5e000
	s_add_u32 s8, s96, s8
	s_addc_u32 s9, s97, 0
	v_mov_b32_e32 v147, 1
	v_mov_b32_e32 v149, 0
	global_atomic_add v151, v149, v147, s[8:9] sc0
	v_mov_b32_e32 v153, 0x125f0
	s_waitcnt vmcnt(0)
	ds_write_b32 v153, v151
	s_waitcnt lgkmcnt(0)
	s_mov_b64 exec, s[6:7]
.Lmgx_wait:
	s_barrier
	v_mov_b32_e32 v153, 0x125f0
	ds_read_b32 v151, v153
	s_waitcnt lgkmcnt(0)
	v_readfirstlane_b32 s12, v151
	s_getreg_b32 s8, hwreg(HW_REG_XCC_ID, 0, 4)
	s_and_b32 s13, s12, 7
	s_lshr_b32 s6, s12, 3
	s_lshl_b32 s6, s6, 3
	s_add_u32 s6, s6, s8
	s_cmp_eq_u32 s18, 0
	s_cbranch_scc0 .Lmg_l1dec
	s_cmpk_lt_u32 s12, 0x110
	s_cbranch_scc0 .Lmg_done
	s_mov_b32 s19, s6
	s_branch .Lmg_decoded
.Lmg_l1dec:
	s_cmpk_lt_u32 s12, 0x100
	s_cbranch_scc0 .Lmg_done
	s_lshr_b32 s7, s6, 5
	s_mul_i32 s7, s7, 34
	s_and_b32 s6, s6, 31
	s_add_u32 s19, s7, s6
	s_add_u32 s19, s19, 2
	s_branch .Lmg_decoded
	s_cmp_eq_u32 s18, 0
	s_cbranch_scc0 .Lmg_static
	s_barrier
	s_cmp_eq_u32 s10, 0
	s_cbranch_scc0 .Lmg_fetch_wait
	s_mov_b64 s[6:7], exec
	s_mov_b64 exec, 1
	s_add_u32 s8, s96, 0x1da5d500
	s_addc_u32 s9, s97, 0
	v_mov_b32_e32 v147, 1
	v_mov_b32_e32 v149, 0
	global_atomic_add v151, v149, v147, s[8:9] sc0
	v_mov_b32_e32 v153, 0x125f0
	s_waitcnt vmcnt(0)
	ds_write_b32 v153, v151
	s_waitcnt lgkmcnt(0)
	s_mov_b64 exec, s[6:7]
